# s5_scan item: hoist the 8 chunk-state loads above the exp/div math (one memory round trip less per scan item), on top of v44
# speedup vs baseline: 1.0068x; 1.0068x over previous
; __device__ void s5_prep_item(const Params& p, int l, int gi, float* lds) {
;     ...
;     if (t < 64) { const int pp = t;
;         const float step = expf(p.log_step[lg]);
;         const float lr = fminf(p.lam_re[lg * 64 + pp], -1e-4f), li = p.lam_im[lg * 64 + pp];
;         const float mag = expf(lr * step); float sn, cs; sincos_small(li * step, sn, cs);
;         const float abr = mag * cs, abi = mag * sn;
;         float pr = 1.f, pi = 0.f;
;         for (int d = 0; d <= 16; ++d) { ap_re[d * 64 + pp] = pr; ap_im[d * 64 + pp] = pi; const float nr_ = pr * abr - pi * abi, ni_ = pr * abi + pi * abr; pr = nr_; pi = ni_; }
;         const float den = lr * lr + li * li, nr = abr - 1.0f, cr = (nr * lr + abi * li) / den, ci = (abi * lr - nr * li) / den;
;         for (int h = 0; h < 16; ++h) { const float br = p.b_re[(lg * 64 + pp) * 16 + h], bi = p.b_im[(lg * 64 + pp) * 16 + h];
;             bb_re[pp * 16 + h] = cr * br - ci * bi; bb_im[pp * 16 + h] = cr * bi + ci * br; }
;         if (part == 0) { float* a16 = (float*)(p.ws + WS_A16) + (g * 64 + pp) * 2; a16[0] = ap_re[16 * 64 + pp]; a16[1] = ap_im[16 * 64 + pp]; }
.LBB0_395:
	s_ashr_i32 s54, s64, 3
	s_and_b32 s33, s64, 7
	s_ashr_i32 s55, s54, 31
	v_mov_b32_e32 v34, v228
	s_add_u32 s40, s14, s54
	s_waitcnt lgkmcnt(0)
	s_barrier
	s_addc_u32 s41, s15, s55
	v_cmp_gt_i32_e32 vcc, 64, v34
	s_and_saveexec_b64 s[42:43], vcc
	s_cbranch_execz .LBB0_404
	v_readlane_b32 s68, v253, 48
	s_lshl_b64 s[56:57], s[40:41], 2
	v_readlane_b32 s80, v253, 60
	v_readlane_b32 s81, v253, 61
	s_add_u32 s56, s80, s56
	s_addc_u32 s57, s81, s57
	global_load_dword v8, v1, s[56:57]
	v_ashrrev_i32_e32 v35, 31, v34
	s_lshl_b64 s[56:57], s[40:41], 6
	v_lshl_add_u64 v[2:3], s[56:57], 0, v[34:35]
	v_readlane_b32 s78, v253, 58
	v_readlane_b32 s79, v253, 59
	v_lshlrev_b64 v[6:7], 2, v[2:3]
	v_readlane_b32 s76, v253, 56
	v_lshl_add_u64 v[4:5], s[78:79], 0, v[6:7]
	global_load_dword v4, v[4:5], off
	v_readlane_b32 s77, v253, 57
	s_mov_b32 s22, 0x3fb8aa3b
	v_readlane_b32 s69, v253, 49
	v_lshl_add_u64 v[6:7], s[76:77], 0, v[6:7]
	global_load_dword v0, v[6:7], off
	v_readlane_b32 s70, v253, 50
	v_readlane_b32 s71, v253, 51
	v_readlane_b32 s72, v253, 52
	v_readlane_b32 s73, v253, 53
	v_readlane_b32 s74, v253, 54
	v_readlane_b32 s75, v253, 55
	v_readlane_b32 s82, v253, 62
	v_readlane_b32 s83, v253, 63
	v_readlane_b32 s100, v252, 0
	v_readlane_b32 s101, v252, 1
	v_lshlrev_b64 v[46:47], 6, v[2:3]
	s_nop 1
	v_lshl_add_u64 v[48:49], s[100:101], 0, v[46:47]
	v_lshl_add_u64 v[50:51], s[82:83], 0, v[46:47]
	global_load_dwordx4 v[52:55], v[48:49], off offset:48
	global_load_dwordx4 v[56:59], v[48:49], off offset:32
	global_load_dwordx4 v[60:63], v[48:49], off offset:16
	global_load_dwordx4 v[64:67], v[48:49], off
	global_load_dwordx4 v[68:71], v[50:51], off offset:48
	global_load_dwordx4 v[72:75], v[50:51], off offset:32
	global_load_dwordx4 v[76:79], v[50:51], off offset:16
	global_load_dwordx4 v[80:83], v[50:51], off
	s_waitcnt vmcnt(10)
	v_mul_f32_e32 v5, 0x3fb8aa3b, v8
	v_fma_f32 v6, v8, s22, -v5
	v_rndne_f32_e32 v7, v5
	v_fmac_f32_e32 v6, 0x32a5705f, v8
	v_sub_f32_e32 v5, v5, v7
	v_add_f32_e32 v5, v5, v6
	v_cvt_i32_f32_e32 v7, v7
	v_exp_f32_e32 v5, v5
	s_mov_b32 s22, 0xc2ce8ed0
	v_cmp_ngt_f32_e32 vcc, s22, v8
	s_mov_b32 s22, 0x42b17218
	v_ldexp_f32 v5, v5, v7
	v_cndmask_b32_e32 v5, 0, v5, vcc
	v_cmp_nlt_f32_e32 vcc, s22, v8
	s_mov_b32 s22, 0x394ca1f9
	s_mov_b32 s23, 0x37ccf5ce
	v_cndmask_b32_e32 v9, v235, v5, vcc
	s_waitcnt vmcnt(9)
	v_mul_f32_e32 v6, v9, v4
	v_mul_f32_e32 v5, 0x3f22f983, v6
	v_rndne_f32_e32 v5, v5
	v_fmac_f32_e32 v6, 0xbfc90000, v5
	v_cvt_i32_f32_e32 v8, v5
	v_fmac_f32_e32 v6, 0xb9fda000, v5
	v_fmac_f32_e32 v6, 0xb3a22169, v5
	v_mul_f32_e32 v7, v6, v6
	v_and_b32_e32 v5, 3, v8
	v_mov_b32_e32 v8, v7
	v_pk_fma_f32 v[12:13], v[8:9], s[22:23], v[200:201] op_sel_hi:[0,1,1] neg_lo:[1,0,0] neg_hi:[1,0,0]
	v_pk_fma_f32 v[14:15], v[8:9], s[22:23], v[200:201] op_sel_hi:[0,1,1]
	s_mov_b32 s22, 0xbe2aaaa3
	v_fma_f32 v16, v7, -0.5, 1.0
	v_mov_b32_e32 v13, v15
	s_mov_b32 s23, 0x3d2aaaa5
	v_pk_mul_f32 v[10:11], v[6:7], v[8:9] op_sel_hi:[1,0]
	v_mov_b32_e32 v7, v16
	v_pk_fma_f32 v[12:13], v[8:9], v[12:13], s[22:23] op_sel_hi:[0,1,1]
	v_pk_fma_f32 v[6:7], v[10:11], v[12:13], v[6:7]
	v_cmp_lt_i32_e32 vcc, 0, v5
	v_mov_b32_e32 v8, v7
	s_and_saveexec_b64 s[56:57], vcc
	s_cbranch_execz .LBB0_402
	v_cmp_ne_u32_e32 vcc, 1, v5
	v_xor_b32_e32 v8, 0x80000000, v6
	s_and_saveexec_b64 s[58:59], vcc
	s_xor_b64 s[58:59], exec, s[58:59]
	v_cmp_eq_u32_e32 vcc, 2, v5
	s_nop 1
	v_cndmask_b32_e32 v5, v7, v6, vcc
	v_xor_b32_e32 v5, 0x80000000, v5
	v_cndmask_b32_e64 v8, v6, -v7, vcc
	v_mov_b32_e32 v6, v5
	s_andn2_saveexec_b64 s[58:59], s[58:59]
	v_mov_b32_e32 v6, v7
	s_or_b64 exec, exec, s[58:59]
.LBB0_402:
	s_or_b64 exec, exec, s[56:57]
	s_waitcnt vmcnt(8)
	v_max_f32_e32 v0, v0, v0
	v_min_f32_e32 v5, 0xb8d1b717, v0
	v_mul_f32_e32 v0, v9, v5
	v_mul_f32_e32 v7, 0x3fb8aa3b, v0
	s_mov_b32 s22, 0x3fb8aa3b
	v_fma_f32 v9, v0, s22, -v7
	v_rndne_f32_e32 v10, v7
	v_fmac_f32_e32 v9, 0x32a5705f, v0
	v_sub_f32_e32 v7, v7, v10
	v_add_f32_e32 v7, v7, v9
	v_exp_f32_e32 v7, v7
	v_cvt_i32_f32_e32 v9, v10
	s_mov_b32 s22, 0xc2ce8ed0
	v_cmp_ngt_f32_e32 vcc, s22, v0
	s_mov_b32 s22, 0x42b17218
	v_ldexp_f32 v7, v7, v9
	v_cndmask_b32_e32 v7, 0, v7, vcc
	v_cmp_nlt_f32_e32 vcc, s22, v0
	v_lshl_add_u32 v0, v34, 2, 0
	v_readlane_b32 s68, v253, 48
	v_cndmask_b32_e32 v7, v235, v7, vcc
	v_mul_f32_e32 v9, v7, v8
	v_mul_f32_e32 v6, v7, v6
	v_fma_f32 v11, 0, v9, v6
	v_fmamk_f32 v10, v6, 0x80000000, v9
	v_mul_f32_e32 v12, v6, v11
	v_mul_f32_e32 v13, v9, v11
	v_fma_f32 v12, v9, v10, -v12
	v_fmac_f32_e32 v13, v6, v10
	ds_write2st64_b32 v0, v232, v10 offset1:1
	ds_write2st64_b32 v0, v11, v13 offset0:18 offset1:19
	v_mul_f32_e32 v10, v6, v13
	v_mul_f32_e32 v11, v6, v12
	v_fma_f32 v10, v9, v12, -v10
	v_fmac_f32_e32 v11, v9, v13
	ds_write2st64_b32 v0, v12, v10 offset0:2 offset1:3
	v_mul_f32_e32 v12, v6, v11
	v_fma_f32 v12, v9, v10, -v12
	v_mul_f32_e32 v10, v6, v10
	v_fmac_f32_e32 v10, v9, v11
	v_mul_f32_e32 v13, v6, v12
	ds_write2st64_b32 v0, v11, v10 offset0:20 offset1:21
	v_mul_f32_e32 v11, v6, v10
	v_fmac_f32_e32 v13, v9, v10
	v_fma_f32 v11, v9, v12, -v11
	v_mul_f32_e32 v10, v6, v13
	ds_write2st64_b32 v0, v12, v11 offset0:4 offset1:5
	v_fma_f32 v10, v9, v11, -v10
	v_mul_f32_e32 v11, v6, v11
	v_fmac_f32_e32 v11, v9, v13
	ds_write2st64_b32 v0, v13, v11 offset0:22 offset1:23
	v_mul_f32_e32 v12, v6, v11
	v_mul_f32_e32 v13, v6, v10
	v_fma_f32 v12, v9, v10, -v12
	v_fmac_f32_e32 v13, v9, v11
	ds_write2st64_b32 v0, v10, v12 offset0:6 offset1:7
	v_mul_f32_e32 v10, v6, v13
	v_mul_f32_e32 v11, v6, v12
	v_fma_f32 v10, v9, v12, -v10
	v_fmac_f32_e32 v11, v9, v13
	ds_write2st64_b32 v0, v13, v11 offset0:24 offset1:25
; __device__ void s5_prep_item(const Params& p, int l, int gi, float* lds) {
;     ...
;         for (int d = 0; d <= 16; ++d) { ap_re[d * 64 + pp] = pr; ap_im[d * 64 + pp] = pi; const float nr_ = pr * abr - pi * abi, ni_ = pr * abi + pi * abr; pr = nr_; pi = ni_; }
;         const float den = lr * lr + li * li, nr = abr - 1.0f, cr = (nr * lr + abi * li) / den, ci = (abi * lr - nr * li) / den;
;         for (int h = 0; h < 16; ++h) { const float br = p.b_re[(lg * 64 + pp) * 16 + h], bi = p.b_im[(lg * 64 + pp) * 16 + h];
;             bb_re[pp * 16 + h] = cr * br - ci * bi; bb_im[pp * 16 + h] = cr * bi + ci * br; }
;         if (part == 0) { float* a16 = (float*)(p.ws + WS_A16) + (g * 64 + pp) * 2; a16[0] = ap_re[16 * 64 + pp]; a16[1] = ap_im[16 * 64 + pp]; }
	v_mul_f32_e32 v12, v6, v11
	v_mul_f32_e32 v13, v6, v10
	v_fma_f32 v12, v9, v10, -v12
	v_fmac_f32_e32 v13, v9, v11
	ds_write2st64_b32 v0, v10, v12 offset0:8 offset1:9
	v_mul_f32_e32 v10, v6, v13
	v_mul_f32_e32 v11, v6, v12
	v_fma_f32 v10, v9, v12, -v10
	v_fmac_f32_e32 v11, v9, v13
	ds_write2st64_b32 v0, v13, v11 offset0:26 offset1:27
	v_mul_f32_e32 v12, v6, v11
	v_mul_f32_e32 v13, v6, v10
	v_fma_f32 v12, v9, v10, -v12
	v_fmac_f32_e32 v13, v9, v11
	ds_write2st64_b32 v0, v10, v12 offset0:10 offset1:11
	v_mul_f32_e32 v10, v6, v13
	v_mul_f32_e32 v11, v6, v12
	v_fma_f32 v10, v9, v12, -v10
	v_fmac_f32_e32 v11, v9, v13
	ds_write2st64_b32 v0, v13, v11 offset0:28 offset1:29
	v_mul_f32_e32 v12, v6, v11
	v_mul_f32_e32 v13, v6, v10
	v_fma_f32 v12, v9, v10, -v12
	v_fmac_f32_e32 v13, v9, v11
	ds_write2st64_b32 v0, v10, v12 offset0:12 offset1:13
	v_mul_f32_e32 v10, v6, v13
	v_mul_f32_e32 v11, v6, v12
	v_fma_f32 v10, v9, v12, -v10
	v_fmac_f32_e32 v11, v9, v13
	ds_write2st64_b32 v0, v13, v11 offset0:30 offset1:31
	v_mul_f32_e32 v12, v6, v11
	v_mul_f32_e32 v13, v6, v10
	v_fma_f32 v12, v9, v10, -v12
	v_fmac_f32_e32 v13, v9, v11
	ds_write2st64_b32 v0, v10, v12 offset0:14 offset1:15
	v_mul_f32_e32 v10, v6, v13
	v_mul_f32_e32 v11, v6, v12
	v_fma_f32 v7, v7, v8, -1.0
	v_fma_f32 v10, v9, v12, -v10
	v_fmac_f32_e32 v11, v9, v13
	v_pk_mul_f32 v[8:9], v[4:5], v[6:7]
	ds_write2st64_b32 v0, v10, v1 offset0:16 offset1:17
	ds_write2st64_b32 v0, v13, v11 offset0:32 offset1:33
	v_add_f32_e32 v12, v8, v9
	v_mov_b32_e32 v8, v5
	v_mov_b32_e32 v10, v6
	v_mov_b32_e32 v11, v5
	v_mov_b32_e32 v6, v7
	v_mov_b32_e32 v7, v4
	v_pk_mul_f32 v[8:9], v[8:9], v[10:11] op_sel_hi:[0,1]
	v_pk_mul_f32 v[4:5], v[4:5], v[6:7] op_sel_hi:[0,1]
	v_add_f32_e32 v5, v9, v5
	v_div_scale_f32 v6, s[56:57], v5, v5, v12
	v_rcp_f32_e32 v7, v6
	v_sub_f32_e32 v4, v8, v4
	v_lshlrev_b64 v[2:3], 6, v[2:3]
	v_readlane_b32 s69, v253, 49
	v_fma_f32 v9, -v6, v7, 1.0
	v_fmac_f32_e32 v7, v9, v7
	v_div_scale_f32 v9, vcc, v12, v5, v12
	v_mul_f32_e32 v10, v9, v7
	v_fma_f32 v11, -v6, v10, v9
	v_fmac_f32_e32 v10, v11, v7
	v_fma_f32 v6, -v6, v10, v9
	v_div_fmas_f32 v6, v6, v7, v10
	v_div_fixup_f32 v36, v6, v5, v12
	v_div_scale_f32 v6, s[56:57], v5, v5, v4
	v_rcp_f32_e32 v7, v6
	v_readlane_b32 s70, v253, 50
	v_readlane_b32 s71, v253, 51
	v_readlane_b32 s72, v253, 52
	v_fma_f32 v8, -v6, v7, 1.0
	v_fmac_f32_e32 v7, v8, v7
	v_div_scale_f32 v8, vcc, v4, v5, v4
	v_mul_f32_e32 v9, v8, v7
	v_fma_f32 v10, -v6, v9, v8
	v_fmac_f32_e32 v9, v10, v7
	v_readlane_b32 s73, v253, 53
	v_readlane_b32 s74, v253, 54
	v_readlane_b32 s75, v253, 55
	v_readlane_b32 s76, v253, 56
	v_readlane_b32 s77, v253, 57
	v_readlane_b32 s78, v253, 58
	v_readlane_b32 s79, v253, 59
	v_readlane_b32 s80, v253, 60
	v_readlane_b32 s81, v253, 61
	v_readlane_b32 s82, v253, 62
	v_readlane_b32 s83, v253, 63
	v_fma_f32 v6, -v6, v9, v8
	v_div_fmas_f32 v6, v6, v7, v9
	v_lshl_add_u64 v[30:31], s[82:83], 0, v[2:3]
	v_readlane_b32 s68, v252, 0
	v_readlane_b32 s69, v252, 1
	v_div_fixup_f32 v38, v6, v5, v4
	v_mad_u64_u32 v[40:41], s[56:57], v34, 60, v[0:1]
	v_lshl_add_u64 v[6:7], s[68:69], 0, v[2:3]
	s_waitcnt vmcnt(0)
	v_mov_b64_e32 v[2:3], v[52:53]
	v_mov_b64_e32 v[4:5], v[54:55]
	v_mov_b64_e32 v[10:11], v[56:57]
	v_mov_b64_e32 v[12:13], v[58:59]
	v_mov_b64_e32 v[18:19], v[60:61]
	v_mov_b64_e32 v[20:21], v[62:63]
	v_mov_b64_e32 v[26:27], v[64:65]
	v_mov_b64_e32 v[28:29], v[66:67]
	v_mov_b64_e32 v[6:7], v[68:69]
	v_mov_b64_e32 v[8:9], v[70:71]
	v_mov_b64_e32 v[14:15], v[72:73]
	v_mov_b64_e32 v[16:17], v[74:75]
	v_mov_b64_e32 v[22:23], v[76:77]
	v_mov_b64_e32 v[24:25], v[78:79]
	v_mov_b64_e32 v[30:31], v[80:81]
	v_mov_b64_e32 v[32:33], v[82:83]
	s_cmp_lg_u32 s33, 0
	v_readlane_b32 s70, v252, 2
	v_readlane_b32 s71, v252, 3
	v_readlane_b32 s72, v252, 4
	v_readlane_b32 s73, v252, 5
	v_readlane_b32 s74, v252, 6
	v_readlane_b32 s75, v252, 7
	v_readlane_b32 s76, v252, 8
	v_readlane_b32 s77, v252, 9
	v_readlane_b32 s78, v252, 10
	v_readlane_b32 s79, v252, 11
	v_readlane_b32 s80, v252, 12
	v_readlane_b32 s81, v252, 13
	v_readlane_b32 s82, v252, 14
	v_readlane_b32 s83, v252, 15
	s_waitcnt vmcnt(4)
	v_pk_mul_f32 v[42:43], v[38:39], v[26:27] op_sel_hi:[0,1]
	v_pk_mul_f32 v[26:27], v[36:37], v[26:27] op_sel_hi:[0,1]
	s_waitcnt vmcnt(0)
	v_pk_fma_f32 v[42:43], v[36:37], v[30:31], v[42:43] op_sel_hi:[0,1,1] neg_lo:[0,0,1] neg_hi:[0,0,1]
	v_pk_fma_f32 v[26:27], v[38:39], v[30:31], v[26:27] op_sel_hi:[0,1,1]
	v_pk_mul_f32 v[30:31], v[38:39], v[28:29] op_sel_hi:[0,1]
	v_pk_mul_f32 v[28:29], v[36:37], v[28:29] op_sel_hi:[0,1]
	v_pk_fma_f32 v[28:29], v[38:39], v[32:33], v[28:29] op_sel_hi:[0,1,1]
	ds_write_b128 v40, v[26:29] offset:12800
	v_pk_mul_f32 v[26:27], v[38:39], v[18:19] op_sel_hi:[0,1]
	v_pk_mul_f32 v[18:19], v[36:37], v[18:19] op_sel_hi:[0,1]
	v_pk_fma_f32 v[26:27], v[36:37], v[22:23], v[26:27] op_sel_hi:[0,1,1] neg_lo:[0,0,1] neg_hi:[0,0,1]
	v_pk_fma_f32 v[18:19], v[38:39], v[22:23], v[18:19] op_sel_hi:[0,1,1]
	v_pk_mul_f32 v[22:23], v[38:39], v[20:21] op_sel_hi:[0,1]
	v_pk_mul_f32 v[20:21], v[36:37], v[20:21] op_sel_hi:[0,1]
	v_pk_fma_f32 v[20:21], v[38:39], v[24:25], v[20:21] op_sel_hi:[0,1,1]
	ds_write_b128 v40, v[18:21] offset:12816
	v_pk_mul_f32 v[18:19], v[38:39], v[10:11] op_sel_hi:[0,1]
	v_pk_mul_f32 v[10:11], v[36:37], v[10:11] op_sel_hi:[0,1]
	v_pk_fma_f32 v[18:19], v[36:37], v[14:15], v[18:19] op_sel_hi:[0,1,1] neg_lo:[0,0,1] neg_hi:[0,0,1]
	v_pk_fma_f32 v[10:11], v[38:39], v[14:15], v[10:11] op_sel_hi:[0,1,1]
	v_pk_mul_f32 v[14:15], v[38:39], v[12:13] op_sel_hi:[0,1]
	v_pk_mul_f32 v[12:13], v[36:37], v[12:13] op_sel_hi:[0,1]
	v_pk_fma_f32 v[12:13], v[38:39], v[16:17], v[12:13] op_sel_hi:[0,1,1]
	ds_write_b128 v40, v[10:13] offset:12832
	v_pk_mul_f32 v[10:11], v[38:39], v[2:3] op_sel_hi:[0,1]
	v_pk_mul_f32 v[2:3], v[36:37], v[2:3] op_sel_hi:[0,1]
	v_pk_fma_f32 v[10:11], v[36:37], v[6:7], v[10:11] op_sel_hi:[0,1,1] neg_lo:[0,0,1] neg_hi:[0,0,1]
	v_pk_fma_f32 v[2:3], v[38:39], v[6:7], v[2:3] op_sel_hi:[0,1,1]
	v_pk_mul_f32 v[6:7], v[38:39], v[4:5] op_sel_hi:[0,1]
	v_pk_mul_f32 v[4:5], v[36:37], v[4:5] op_sel_hi:[0,1]
	v_pk_fma_f32 v[44:45], v[36:37], v[32:33], v[30:31] op_sel_hi:[0,1,1] neg_lo:[0,0,1] neg_hi:[0,0,1]
	v_pk_fma_f32 v[28:29], v[36:37], v[24:25], v[22:23] op_sel_hi:[0,1,1] neg_lo:[0,0,1] neg_hi:[0,0,1]
	v_pk_fma_f32 v[20:21], v[36:37], v[16:17], v[14:15] op_sel_hi:[0,1,1] neg_lo:[0,0,1] neg_hi:[0,0,1]
	v_pk_fma_f32 v[12:13], v[36:37], v[8:9], v[6:7] op_sel_hi:[0,1,1] neg_lo:[0,0,1] neg_hi:[0,0,1]
	v_pk_fma_f32 v[4:5], v[38:39], v[8:9], v[4:5] op_sel_hi:[0,1,1]
	ds_write_b128 v40, v[42:45] offset:8704
	ds_write_b128 v40, v[26:29] offset:8720
	ds_write_b128 v40, v[18:21] offset:8736
	ds_write_b128 v40, v[10:13] offset:8752
	ds_write_b128 v40, v[2:5] offset:12848
	s_cbranch_scc1 .LBB0_404
	ds_read2st64_b32 v[4:5], v0 offset0:16 offset1:33
	s_lshl_b32 s22, s54, 7
	v_lshl_add_u32 v2, v34, 1, s22
	v_ashrrev_i32_e32 v3, 31, v2
	v_lshl_add_u64 v[2:3], v[2:3], 2, s[18:19]
	s_waitcnt lgkmcnt(0)
	global_store_dwordx2 v[2:3], v[4:5], off
